# SwiGLU epilogue: one 16-byte store per row and lane (FFN-in weight columns reassigned so a lane's two output groups are adjacent)
# speedup vs baseline: 1.0542x; 1.0076x over previous
;     __device__ __forceinline__ void operator()(const f32x4 (&acc)[2][2][4][2], const pg8::Unit& u, int wr, int wc, int fr, int fq) const {
;         const int row0 = u.pm * 256 + wr * 64 + fr, col0 = (u.pn * 256 + wc * 32 + 8 * fq) >> 1;
; #pragma unroll
;         for (int ai = 0; ai < 2; ++ai)
; #pragma unroll
;             for (int m = 0; m < 4; ++m) {
;                 bf16_t* rowp = O + (size_t)(row0 + ai * 128 + m * 16) * FFH + col0;
.LBB0_46:
	v_lshlrev_b32_e32 v158, 1, v144
	v_lshl_or_b32 v158, s16, 8, v158
	v_lshl_add_u32 v146, s48, 8, v142
	s_movk_i32 s4, 0x1600
	v_mov_b32_e32 v172, 0xbfb8aa3b
	v_mov_b32_e32 v173, 0xbfb8aa3b
	v_mad_u32_u24 v160, v146, s4, v158
	v_add_u32_e32 v161, 0x16000, v160
	v_add_u32_e32 v162, 0x2c000, v160
	v_add_u32_e32 v163, 0x42000, v160
	v_add_u32_e32 v164, 0xb0000, v160
	v_add_u32_e32 v165, 0xc6000, v160
	v_add_u32_e32 v166, 0xdc000, v160
	v_add_u32_e32 v167, 0xf2000, v160

; __device__ __forceinline__ unsigned cvt_pk_bf16(float lo, float hi) { unsigned r; asm volatile("v_cvt_pk_bf16_f32 %0, %1, %2" : "=v"(r) : "v"(lo), "v"(hi)); return r; }
; __device__ __forceinline__ float silu_f(float v) { return v * __builtin_amdgcn_rcpf(1.f + __builtin_amdgcn_exp2f(-v * LOG2E)); }
;     __device__ __forceinline__ void operator()(const f32x4 (&acc)[2][2][4][2], const pg8::Unit& u, int wr, int wc, int fr, int fq) const {
;     ...
;         for (int ai = 0; ai < 2; ++ai)
; #pragma unroll
;             for (int m = 0; m < 4; ++m) {
;                 bf16_t* rowp = O + (size_t)(row0 + ai * 128 + m * 16) * FFH + col0;
; #pragma unroll
;                 for (int bj = 0; bj < 2; ++bj) {
;                     const f32x4 a = acc[ai][bj][m][0], b = acc[ai][bj][m][1];
;                     u32x2 w; w.x = cvt_pk_bf16(silu_f(a[0]) * b[0], silu_f(a[1]) * b[1]); w.y = cvt_pk_bf16(silu_f(a[2]) * b[2], silu_f(a[3]) * b[3]);
;                     *(u32x2*)(rowp + bj * 64) = w;
;                 }
	v_pk_mul_f32 v[146:147], v[124:125], v[172:173]
	v_pk_mul_f32 v[148:149], v[126:127], v[172:173]
	v_pk_mul_f32 v[150:151], v[116:117], v[172:173]
	v_pk_mul_f32 v[152:153], v[118:119], v[172:173]
	v_exp_f32_e32 v146, v146
	v_exp_f32_e32 v147, v147
	v_exp_f32_e32 v148, v148
	v_exp_f32_e32 v149, v149
	v_exp_f32_e32 v150, v150
	v_exp_f32_e32 v151, v151
	v_exp_f32_e32 v152, v152
	v_exp_f32_e32 v153, v153
	v_pk_add_f32 v[146:147], v[146:147], 1.0 op_sel_hi:[1,0]
	v_pk_add_f32 v[148:149], v[148:149], 1.0 op_sel_hi:[1,0]
	v_pk_add_f32 v[150:151], v[150:151], 1.0 op_sel_hi:[1,0]
	v_pk_add_f32 v[152:153], v[152:153], 1.0 op_sel_hi:[1,0]
	v_rcp_f32_e32 v146, v146
	v_rcp_f32_e32 v147, v147
	v_rcp_f32_e32 v148, v148
	v_rcp_f32_e32 v149, v149
	v_rcp_f32_e32 v150, v150
	v_rcp_f32_e32 v151, v151
	v_rcp_f32_e32 v152, v152
	v_rcp_f32_e32 v153, v153
	v_pk_mul_f32 v[124:125], v[124:125], v[146:147]
	v_pk_mul_f32 v[126:127], v[126:127], v[148:149]
	v_pk_mul_f32 v[116:117], v[116:117], v[150:151]
	v_pk_mul_f32 v[118:119], v[118:119], v[152:153]
	v_pk_mul_f32 v[120:121], v[120:121], v[124:125]
	v_pk_mul_f32 v[122:123], v[122:123], v[126:127]
	v_pk_mul_f32 v[112:113], v[112:113], v[116:117]
	v_pk_mul_f32 v[114:115], v[114:115], v[118:119]
	v_cvt_pk_bf16_f32 v154, v120, v121
	v_cvt_pk_bf16_f32 v156, v112, v113
	v_cvt_pk_bf16_f32 v155, v122, v123
	v_cvt_pk_bf16_f32 v157, v114, v115
	global_store_dwordx4 v160, v[154:157], s[18:19]
	v_pk_mul_f32 v[146:147], v[108:109], v[172:173]
	v_pk_mul_f32 v[148:149], v[110:111], v[172:173]
	v_pk_mul_f32 v[150:151], v[100:101], v[172:173]
	v_pk_mul_f32 v[152:153], v[102:103], v[172:173]
	v_exp_f32_e32 v146, v146
	v_exp_f32_e32 v147, v147
	v_exp_f32_e32 v148, v148
	v_exp_f32_e32 v149, v149
	v_exp_f32_e32 v150, v150
	v_exp_f32_e32 v151, v151
	v_exp_f32_e32 v152, v152
	v_exp_f32_e32 v153, v153
	v_pk_add_f32 v[146:147], v[146:147], 1.0 op_sel_hi:[1,0]
	v_pk_add_f32 v[148:149], v[148:149], 1.0 op_sel_hi:[1,0]
	v_pk_add_f32 v[150:151], v[150:151], 1.0 op_sel_hi:[1,0]
	v_pk_add_f32 v[152:153], v[152:153], 1.0 op_sel_hi:[1,0]
	v_rcp_f32_e32 v146, v146
	v_rcp_f32_e32 v147, v147
	v_rcp_f32_e32 v148, v148
	v_rcp_f32_e32 v149, v149
	v_rcp_f32_e32 v150, v150
	v_rcp_f32_e32 v151, v151
	v_rcp_f32_e32 v152, v152
	v_rcp_f32_e32 v153, v153
	v_pk_mul_f32 v[108:109], v[108:109], v[146:147]
	v_pk_mul_f32 v[110:111], v[110:111], v[148:149]
	v_pk_mul_f32 v[100:101], v[100:101], v[150:151]
	v_pk_mul_f32 v[102:103], v[102:103], v[152:153]
	v_pk_mul_f32 v[104:105], v[104:105], v[108:109]
	v_pk_mul_f32 v[106:107], v[106:107], v[110:111]
	v_pk_mul_f32 v[96:97], v[96:97], v[100:101]
	v_pk_mul_f32 v[98:99], v[98:99], v[102:103]
	v_cvt_pk_bf16_f32 v168, v104, v105
	v_cvt_pk_bf16_f32 v170, v96, v97
	v_cvt_pk_bf16_f32 v169, v106, v107
	v_cvt_pk_bf16_f32 v171, v98, v99
	global_store_dwordx4 v161, v[168:171], s[18:19]
	v_pk_mul_f32 v[146:147], v[92:93], v[172:173]
	v_pk_mul_f32 v[148:149], v[94:95], v[172:173]
	v_pk_mul_f32 v[150:151], v[84:85], v[172:173]
	v_pk_mul_f32 v[152:153], v[86:87], v[172:173]
	v_exp_f32_e32 v146, v146
	v_exp_f32_e32 v147, v147
	v_exp_f32_e32 v148, v148
	v_exp_f32_e32 v149, v149
	v_exp_f32_e32 v150, v150
	v_exp_f32_e32 v151, v151
	v_exp_f32_e32 v152, v152
	v_exp_f32_e32 v153, v153
	v_pk_add_f32 v[146:147], v[146:147], 1.0 op_sel_hi:[1,0]
	v_pk_add_f32 v[148:149], v[148:149], 1.0 op_sel_hi:[1,0]
	v_pk_add_f32 v[150:151], v[150:151], 1.0 op_sel_hi:[1,0]
	v_pk_add_f32 v[152:153], v[152:153], 1.0 op_sel_hi:[1,0]
	v_rcp_f32_e32 v146, v146
	v_rcp_f32_e32 v147, v147
	v_rcp_f32_e32 v148, v148
	v_rcp_f32_e32 v149, v149
	v_rcp_f32_e32 v150, v150
	v_rcp_f32_e32 v151, v151
	v_rcp_f32_e32 v152, v152
	v_rcp_f32_e32 v153, v153
	v_pk_mul_f32 v[92:93], v[92:93], v[146:147]
	v_pk_mul_f32 v[94:95], v[94:95], v[148:149]
	v_pk_mul_f32 v[84:85], v[84:85], v[150:151]
	v_pk_mul_f32 v[86:87], v[86:87], v[152:153]
	v_pk_mul_f32 v[88:89], v[88:89], v[92:93]
	v_pk_mul_f32 v[90:91], v[90:91], v[94:95]
	v_pk_mul_f32 v[80:81], v[80:81], v[84:85]
	v_pk_mul_f32 v[82:83], v[82:83], v[86:87]
	v_cvt_pk_bf16_f32 v154, v88, v89
	v_cvt_pk_bf16_f32 v156, v80, v81
	v_cvt_pk_bf16_f32 v155, v90, v91
	v_cvt_pk_bf16_f32 v157, v82, v83
	global_store_dwordx4 v162, v[154:157], s[18:19]
	v_pk_mul_f32 v[146:147], v[76:77], v[172:173]
	v_pk_mul_f32 v[148:149], v[78:79], v[172:173]
	v_pk_mul_f32 v[150:151], v[68:69], v[172:173]
	v_pk_mul_f32 v[152:153], v[70:71], v[172:173]
	v_exp_f32_e32 v146, v146
	v_exp_f32_e32 v147, v147
	v_exp_f32_e32 v148, v148
	v_exp_f32_e32 v149, v149
	v_exp_f32_e32 v150, v150
	v_exp_f32_e32 v151, v151
	v_exp_f32_e32 v152, v152
	v_exp_f32_e32 v153, v153
	v_pk_add_f32 v[146:147], v[146:147], 1.0 op_sel_hi:[1,0]
	v_pk_add_f32 v[148:149], v[148:149], 1.0 op_sel_hi:[1,0]
	v_pk_add_f32 v[150:151], v[150:151], 1.0 op_sel_hi:[1,0]
	v_pk_add_f32 v[152:153], v[152:153], 1.0 op_sel_hi:[1,0]
	v_rcp_f32_e32 v146, v146
	v_rcp_f32_e32 v147, v147
	v_rcp_f32_e32 v148, v148
	v_rcp_f32_e32 v149, v149
	v_rcp_f32_e32 v150, v150
	v_rcp_f32_e32 v151, v151
	v_rcp_f32_e32 v152, v152
	v_rcp_f32_e32 v153, v153
	v_pk_mul_f32 v[76:77], v[76:77], v[146:147]
	v_pk_mul_f32 v[78:79], v[78:79], v[148:149]
	v_pk_mul_f32 v[68:69], v[68:69], v[150:151]
	v_pk_mul_f32 v[70:71], v[70:71], v[152:153]
	v_pk_mul_f32 v[72:73], v[72:73], v[76:77]
	v_pk_mul_f32 v[74:75], v[74:75], v[78:79]
	v_pk_mul_f32 v[64:65], v[64:65], v[68:69]
	v_pk_mul_f32 v[66:67], v[66:67], v[70:71]
	v_cvt_pk_bf16_f32 v168, v72, v73
	v_cvt_pk_bf16_f32 v170, v64, v65
	v_cvt_pk_bf16_f32 v169, v74, v75
	v_cvt_pk_bf16_f32 v171, v66, v67
; __device__ __forceinline__ unsigned cvt_pk_bf16(float lo, float hi) { unsigned r; asm volatile("v_cvt_pk_bf16_f32 %0, %1, %2" : "=v"(r) : "v"(lo), "v"(hi)); return r; }
; __device__ __forceinline__ float silu_f(float v) { return v * __builtin_amdgcn_rcpf(1.f + __builtin_amdgcn_exp2f(-v * LOG2E)); }
;     __device__ __forceinline__ void operator()(const f32x4 (&acc)[2][2][4][2], const pg8::Unit& u, int wr, int wc, int fr, int fq) const {
;     ...
;         for (int ai = 0; ai < 2; ++ai)
; #pragma unroll
;             for (int m = 0; m < 4; ++m) {
;                 bf16_t* rowp = O + (size_t)(row0 + ai * 128 + m * 16) * FFH + col0;
; #pragma unroll
;                 for (int bj = 0; bj < 2; ++bj) {
;                     const f32x4 a = acc[ai][bj][m][0], b = acc[ai][bj][m][1];
;                     u32x2 w; w.x = cvt_pk_bf16(silu_f(a[0]) * b[0], silu_f(a[1]) * b[1]); w.y = cvt_pk_bf16(silu_f(a[2]) * b[2], silu_f(a[3]) * b[3]);
;                     *(u32x2*)(rowp + bj * 64) = w;
;                 }
	global_store_dwordx4 v163, v[168:171], s[18:19]
	v_pk_mul_f32 v[146:147], v[60:61], v[172:173]
	v_pk_mul_f32 v[148:149], v[62:63], v[172:173]
	v_pk_mul_f32 v[150:151], v[52:53], v[172:173]
	v_pk_mul_f32 v[152:153], v[54:55], v[172:173]
	v_exp_f32_e32 v146, v146
	v_exp_f32_e32 v147, v147
	v_exp_f32_e32 v148, v148
	v_exp_f32_e32 v149, v149
	v_exp_f32_e32 v150, v150
	v_exp_f32_e32 v151, v151
	v_exp_f32_e32 v152, v152
	v_exp_f32_e32 v153, v153
	v_pk_add_f32 v[146:147], v[146:147], 1.0 op_sel_hi:[1,0]
	v_pk_add_f32 v[148:149], v[148:149], 1.0 op_sel_hi:[1,0]
	v_pk_add_f32 v[150:151], v[150:151], 1.0 op_sel_hi:[1,0]
	v_pk_add_f32 v[152:153], v[152:153], 1.0 op_sel_hi:[1,0]
	v_rcp_f32_e32 v146, v146
	v_rcp_f32_e32 v147, v147
	v_rcp_f32_e32 v148, v148
	v_rcp_f32_e32 v149, v149
	v_rcp_f32_e32 v150, v150
	v_rcp_f32_e32 v151, v151
	v_rcp_f32_e32 v152, v152
	v_rcp_f32_e32 v153, v153
	v_pk_mul_f32 v[60:61], v[60:61], v[146:147]
	v_pk_mul_f32 v[62:63], v[62:63], v[148:149]
	v_pk_mul_f32 v[52:53], v[52:53], v[150:151]
	v_pk_mul_f32 v[54:55], v[54:55], v[152:153]
	v_pk_mul_f32 v[56:57], v[56:57], v[60:61]
	v_pk_mul_f32 v[58:59], v[58:59], v[62:63]
	v_pk_mul_f32 v[48:49], v[48:49], v[52:53]
	v_pk_mul_f32 v[50:51], v[50:51], v[54:55]
	v_cvt_pk_bf16_f32 v154, v56, v57
	v_cvt_pk_bf16_f32 v156, v48, v49
	v_cvt_pk_bf16_f32 v155, v58, v59
	v_cvt_pk_bf16_f32 v157, v50, v51
	global_store_dwordx4 v164, v[154:157], s[18:19]
	v_pk_mul_f32 v[146:147], v[44:45], v[172:173]
	v_pk_mul_f32 v[148:149], v[46:47], v[172:173]
	v_pk_mul_f32 v[150:151], v[36:37], v[172:173]
	v_pk_mul_f32 v[152:153], v[38:39], v[172:173]
	v_exp_f32_e32 v146, v146
	v_exp_f32_e32 v147, v147
	v_exp_f32_e32 v148, v148
	v_exp_f32_e32 v149, v149
	v_exp_f32_e32 v150, v150
	v_exp_f32_e32 v151, v151
	v_exp_f32_e32 v152, v152
	v_exp_f32_e32 v153, v153
	v_pk_add_f32 v[146:147], v[146:147], 1.0 op_sel_hi:[1,0]
	v_pk_add_f32 v[148:149], v[148:149], 1.0 op_sel_hi:[1,0]
	v_pk_add_f32 v[150:151], v[150:151], 1.0 op_sel_hi:[1,0]
	v_pk_add_f32 v[152:153], v[152:153], 1.0 op_sel_hi:[1,0]
	v_rcp_f32_e32 v146, v146
	v_rcp_f32_e32 v147, v147
	v_rcp_f32_e32 v148, v148
	v_rcp_f32_e32 v149, v149
	v_rcp_f32_e32 v150, v150
	v_rcp_f32_e32 v151, v151
	v_rcp_f32_e32 v152, v152
	v_rcp_f32_e32 v153, v153
	v_pk_mul_f32 v[44:45], v[44:45], v[146:147]
	v_pk_mul_f32 v[46:47], v[46:47], v[148:149]
	v_pk_mul_f32 v[36:37], v[36:37], v[150:151]
	v_pk_mul_f32 v[38:39], v[38:39], v[152:153]
	v_pk_mul_f32 v[40:41], v[40:41], v[44:45]
	v_pk_mul_f32 v[42:43], v[42:43], v[46:47]
	v_pk_mul_f32 v[32:33], v[32:33], v[36:37]
	v_pk_mul_f32 v[34:35], v[34:35], v[38:39]
	v_cvt_pk_bf16_f32 v168, v40, v41
	v_cvt_pk_bf16_f32 v170, v32, v33
	v_cvt_pk_bf16_f32 v169, v42, v43
	v_cvt_pk_bf16_f32 v171, v34, v35
	global_store_dwordx4 v165, v[168:171], s[18:19]
	v_pk_mul_f32 v[146:147], v[28:29], v[172:173]
	v_pk_mul_f32 v[148:149], v[30:31], v[172:173]
	v_pk_mul_f32 v[150:151], v[20:21], v[172:173]
	v_pk_mul_f32 v[152:153], v[22:23], v[172:173]
	v_exp_f32_e32 v146, v146
	v_exp_f32_e32 v147, v147
	v_exp_f32_e32 v148, v148
	v_exp_f32_e32 v149, v149
	v_exp_f32_e32 v150, v150
	v_exp_f32_e32 v151, v151
	v_exp_f32_e32 v152, v152
	v_exp_f32_e32 v153, v153
	v_pk_add_f32 v[146:147], v[146:147], 1.0 op_sel_hi:[1,0]
	v_pk_add_f32 v[148:149], v[148:149], 1.0 op_sel_hi:[1,0]
	v_pk_add_f32 v[150:151], v[150:151], 1.0 op_sel_hi:[1,0]
	v_pk_add_f32 v[152:153], v[152:153], 1.0 op_sel_hi:[1,0]
	v_rcp_f32_e32 v146, v146
	v_rcp_f32_e32 v147, v147
	v_rcp_f32_e32 v148, v148
	v_rcp_f32_e32 v149, v149
	v_rcp_f32_e32 v150, v150
	v_rcp_f32_e32 v151, v151
	v_rcp_f32_e32 v152, v152
	v_rcp_f32_e32 v153, v153
	v_pk_mul_f32 v[28:29], v[28:29], v[146:147]
	v_pk_mul_f32 v[30:31], v[30:31], v[148:149]
	v_pk_mul_f32 v[20:21], v[20:21], v[150:151]
	v_pk_mul_f32 v[22:23], v[22:23], v[152:153]
	v_pk_mul_f32 v[24:25], v[24:25], v[28:29]
	v_pk_mul_f32 v[26:27], v[26:27], v[30:31]
	v_pk_mul_f32 v[16:17], v[16:17], v[20:21]
	v_pk_mul_f32 v[18:19], v[18:19], v[22:23]
	v_cvt_pk_bf16_f32 v154, v24, v25
	v_cvt_pk_bf16_f32 v156, v16, v17
	v_cvt_pk_bf16_f32 v155, v26, v27
	v_cvt_pk_bf16_f32 v157, v18, v19
	global_store_dwordx4 v166, v[154:157], s[18:19]
	v_pk_mul_f32 v[146:147], v[12:13], v[172:173]
	v_pk_mul_f32 v[148:149], v[14:15], v[172:173]
	v_pk_mul_f32 v[150:151], v[4:5], v[172:173]
	v_pk_mul_f32 v[152:153], v[6:7], v[172:173]
	v_exp_f32_e32 v146, v146
	v_exp_f32_e32 v147, v147
	v_exp_f32_e32 v148, v148
	v_exp_f32_e32 v149, v149
	v_exp_f32_e32 v150, v150
	v_exp_f32_e32 v151, v151
	v_exp_f32_e32 v152, v152
	v_exp_f32_e32 v153, v153
	v_pk_add_f32 v[146:147], v[146:147], 1.0 op_sel_hi:[1,0]
	v_pk_add_f32 v[148:149], v[148:149], 1.0 op_sel_hi:[1,0]
	v_pk_add_f32 v[150:151], v[150:151], 1.0 op_sel_hi:[1,0]
	v_pk_add_f32 v[152:153], v[152:153], 1.0 op_sel_hi:[1,0]
	v_rcp_f32_e32 v146, v146
	v_rcp_f32_e32 v147, v147
	v_rcp_f32_e32 v148, v148
	v_rcp_f32_e32 v149, v149
	v_rcp_f32_e32 v150, v150
	v_rcp_f32_e32 v151, v151
	v_rcp_f32_e32 v152, v152
	v_rcp_f32_e32 v153, v153
	v_pk_mul_f32 v[12:13], v[12:13], v[146:147]
	v_pk_mul_f32 v[14:15], v[14:15], v[148:149]
	v_pk_mul_f32 v[4:5], v[4:5], v[150:151]
	v_pk_mul_f32 v[6:7], v[6:7], v[152:153]
	v_pk_mul_f32 v[8:9], v[8:9], v[12:13]
	v_pk_mul_f32 v[10:11], v[10:11], v[14:15]
	v_pk_mul_f32 v[0:1], v[0:1], v[4:5]
	v_pk_mul_f32 v[2:3], v[2:3], v[6:7]
	v_cvt_pk_bf16_f32 v168, v8, v9
	v_cvt_pk_bf16_f32 v170, v0, v1
	v_cvt_pk_bf16_f32 v169, v10, v11
	v_cvt_pk_bf16_f32 v171, v2, v3
	global_store_dwordx4 v167, v[168:171], s[18:19]
	s_andn2_b64 vcc, exec, s[54:55]
	s_mov_b64 s[2:3], -1
	s_cbranch_vccnz .LBB0_39

; #define PG8_BAR __builtin_amdgcn_s_barrier()
; template <class Epi, class Sched, bool ALIGN_EPI = false, bool SP2 = false>
; __device__ __forceinline__ void gemm_phase(PG8_LAS unsigned char* lds, const Gemm g, const Sched& S, const Epi& E) {
;     ...
;         if constexpr (ALIGN_EPI) { if (wr == 1) PG8_BAR; }
;     }
	s_andn2_b64 vcc, exec, s[38:39]
	s_cbranch_vccnz .LBB0_38
	s_barrier
	s_branch .LBB0_38

; __device__ __forceinline__ int srccol(int g, int lim, int grp, int P) {
;     if (g >= lim) return g;
;     const int base = (g / grp) * grp, gl = g - base, u = gl >> 3, j = gl & 7;
;     return base + 4 * u + (j & 3) + P * (j >> 2);
; }
; __device__ __forceinline__ void cvt_item(const float* __restrict__ W, int K, int N, bf16_t* WT, float* scr, int item, int lane, int lim, int grp, int P) {
;     const int nblk = N / 32, kb = item / nblk, nb = item - kb * nblk, k0 = 64 * kb, n0 = 32 * nb;
;     const int sc = srccol(n0 + (lane & 31), lim, grp, P);
.LBB0_1067:
	s_and_b64 vcc, exec, s[2:3]
	s_cbranch_vccz .LBB0_1084
	s_mul_hi_i32 s2, s5, 0x2e8ba2e9
	s_lshr_b32 s3, s2, 31
	s_ashr_i32 s6, s2, 5
	s_add_i32 s6, s6, s3
	s_mul_i32 s2, s6, 0xffffff50
	s_add_i32 s2, s2, s5
	s_lshl_b32 s5, s2, 5
	v_or_b32_e32 v14, s5, v17
	s_movk_i32 s2, 0x1600
	v_cmp_gt_i32_e32 vcc, s2, v14
	s_and_saveexec_b64 s[2:3], vcc
	s_cbranch_execz .LBB0_1070
	s_mov_b32 s7, 0x2e8ba2e9
	v_mul_hi_i32 v3, v14, s7
	v_lshrrev_b32_e32 v15, 31, v3
	v_ashrrev_i32_e32 v3, 10, v3
	v_add_u32_e32 v3, v3, v15
	v_mul_i32_i24_e32 v3, 0x1600, v3
	v_sub_u32_e32 v14, v14, v3
	v_ashrrev_i32_e32 v15, 1, v14
	v_bfe_i32 v16, v14, 2, 1
	v_and_b32_e32 v15, -4, v15
	v_bfe_u32 v106, v15, 2, 5
	v_lshlrev_b32_e32 v107, 1, v106
	v_and_b32_e32 v107, 30, v107
	v_lshrrev_b32_e32 v106, 4, v106
	v_or_b32_e32 v106, v106, v107
	v_and_b32_e32 v15, 0xffffff83, v15
	v_lshl_or_b32 v15, v106, 2, v15

; __device__ __forceinline__ int srccol(int g, int lim, int grp, int P) {
;     ...
;     return base + 4 * u + (j & 3) + P * (j >> 2);
	v_and_b32_e32 v16, 0xb00, v16
	v_and_or_b32 v3, v14, 3, v3
	v_add3_u32 v14, v3, v15, v16
